# v94 plus nt hint on the write-once f32 output stores of the final RMSNorm rows
# baseline (speedup 1.0000x reference)
; __device__ __forceinline__ float rs_of(float ss) { return 1.0f / sqrtf(ss * (1.f / 1024.f) + 1e-6f); }
; __device__ __forceinline__ void final_rows(const bf16_t* XB, float* out, const float* g, const float* SS, int gw, int NGW, int lane) {
;     ...
; #pragma unroll
;         for (int q = 0; q < 4; ++q) { float t = tp[q]; t += __shfl_xor(t, 1); t += __shfl_xor(t, 2); t += __shfl_xor(t, 4); t += __shfl_xor(t, 8); const float r = rs_of(__shfl(t, 0));
;             f32x4* o = (f32x4*)(out + (size_t)(m0 + q) * D) + lane;
; #pragma unroll
;             for (int j = 0; j < 4; ++j) o[64 * j] = (f32x4){bf_lo(w[q][j].x), bf_hi(w[q][j].x), bf_lo(w[q][j].y), bf_hi(w[q][j].y)} * r * gv[j]; } }
.LBB0_1905:
	s_or_b64 exec, exec, s[2:3]
	s_waitcnt vmcnt(0)
	ds_bpermute_b32 v54, v56, v66
	v_lshlrev_b32_e32 v68, 16, v50
	v_and_b32_e32 v71, 0xffff0000, v51
	s_add_i32 s4, s4, s6
	v_lshl_add_u64 v[18:19], v[18:19], 0, s[10:11]
	s_waitcnt lgkmcnt(0)
	v_add_f32_e32 v54, v66, v54
	ds_bpermute_b32 v55, v57, v54
	s_bfe_u32 s99, s4, 0x20005
	s_cmp_lg_u32 s99, 0
	s_cselect_b32 s99, 1, 0
	s_cmp_lt_i32 s4, 0x8000
	s_cselect_b32 s100, 1, 0
	s_cmp_lg_u32 s98, 0
	s_cselect_b32 s99, s99, s100
	s_cmp_lg_u32 s99, 0
	v_lshl_add_u64 v[20:21], v[20:21], 0, s[12:13]
	s_waitcnt lgkmcnt(0)
	v_add_f32_e32 v54, v54, v55
	ds_bpermute_b32 v55, v58, v54
	s_waitcnt lgkmcnt(0)
	v_add_f32_e32 v66, v54, v55
	ds_bpermute_b32 v67, v59, v66
	v_lshlrev_b32_e32 v54, 16, v52
	v_and_b32_e32 v55, 0xffff0000, v52
	v_lshlrev_b32_e32 v52, 16, v53
	v_and_b32_e32 v53, 0xffff0000, v53
	s_waitcnt lgkmcnt(0)
	v_add_f32_e32 v66, v66, v67
	ds_bpermute_b32 v69, v60, v66
	v_add_co_u32_e32 v66, vcc, s7, v16
	s_waitcnt lgkmcnt(0)
	v_fmamk_f32 v69, v69, 0x3a800000, v61
	v_addc_co_u32_e32 v67, vcc, -1, v17, vcc
	v_mul_f32_e32 v70, 0x4f800000, v69
	v_cmp_gt_f32_e32 vcc, s5, v69
	s_nop 1
	v_cndmask_b32_e32 v72, v69, v70, vcc
	v_sqrt_f32_e32 v73, v72
	v_and_b32_e32 v69, 0xffff0000, v50
	v_lshlrev_b32_e32 v70, 16, v51
	v_add_u32_e32 v50, -1, v73
	v_add_u32_e32 v51, 1, v73
	v_fma_f32 v74, -v50, v73, v72
	v_fma_f32 v75, -v51, v73, v72
	v_cmp_ge_f32_e64 s[2:3], 0, v74
	s_nop 1
	v_cndmask_b32_e64 v50, v73, v50, s[2:3]
	v_cmp_lt_f32_e64 s[2:3], 0, v75
	ds_bpermute_b32 v73, v56, v65
	s_waitcnt lgkmcnt(0)
	v_add_f32_e32 v65, v65, v73
	v_cndmask_b32_e64 v50, v50, v51, s[2:3]
	v_mul_f32_e32 v51, 0x37800000, v50
	v_cndmask_b32_e32 v50, v50, v51, vcc
	v_cmp_class_f32_e32 vcc, v72, v62
	s_nop 1
	v_cndmask_b32_e32 v50, v50, v72, vcc
	v_div_scale_f32 v51, s[2:3], v50, v50, 1.0
	v_rcp_f32_e32 v72, v51
	v_div_scale_f32 v74, vcc, 1.0, v50, 1.0
	v_fma_f32 v75, -v51, v72, 1.0
	v_fmac_f32_e32 v72, v75, v72
	v_mul_f32_e32 v75, v74, v72
	v_fma_f32 v76, -v51, v75, v74
	v_fmac_f32_e32 v75, v76, v72
	v_fma_f32 v51, -v51, v75, v74
	v_div_fmas_f32 v51, v51, v72, v75
	v_div_fixup_f32 v72, v51, v50, 1.0
	v_pk_mul_f32 v[50:51], v[72:73], v[54:55] op_sel_hi:[0,1]
	v_pk_mul_f32 v[54:55], v[72:73], v[68:69] op_sel_hi:[0,1]
	ds_bpermute_b32 v68, v57, v65
	v_pk_mul_f32 v[52:53], v[72:73], v[52:53] op_sel_hi:[0,1]
	v_pk_mul_f32 v[52:53], v[2:3], v[52:53]
	v_pk_mul_f32 v[50:51], v[0:1], v[50:51]
	global_store_dwordx4 v[66:67], v[50:53], off offset:-3072 nt
	s_nop 1
	v_pk_mul_f32 v[50:51], v[72:73], v[70:71] op_sel_hi:[0,1]
	v_pk_mul_f32 v[52:53], v[6:7], v[50:51]
	v_pk_mul_f32 v[50:51], v[4:5], v[54:55]
	s_waitcnt lgkmcnt(0)
	v_add_f32_e32 v54, v65, v68
	ds_bpermute_b32 v55, v58, v54
	global_store_dwordx4 v[66:67], v[50:53], off offset:-2048 nt
	s_waitcnt lgkmcnt(0)
	v_add_f32_e32 v54, v54, v55
	ds_bpermute_b32 v55, v59, v54
	v_lshlrev_b32_e32 v50, 16, v48
	v_and_b32_e32 v51, 0xffff0000, v48
	v_lshlrev_b32_e32 v48, 16, v49
	v_and_b32_e32 v49, 0xffff0000, v49
	v_pk_mul_f32 v[52:53], v[72:73], v[50:51] op_sel_hi:[0,1]
	v_pk_mul_f32 v[48:49], v[72:73], v[48:49] op_sel_hi:[0,1]
	v_pk_mul_f32 v[50:51], v[10:11], v[48:49]
	v_pk_mul_f32 v[48:49], v[8:9], v[52:53]
	global_store_dwordx4 v[66:67], v[48:51], off offset:-1024 nt
	s_waitcnt lgkmcnt(0)
	s_nop 0
	v_add_f32_e32 v49, v54, v55
	ds_bpermute_b32 v52, v60, v49
	v_lshlrev_b32_e32 v48, 16, v46
	v_and_b32_e32 v49, 0xffff0000, v46
	v_pk_mul_f32 v[50:51], v[72:73], v[48:49] op_sel_hi:[0,1]
	v_lshlrev_b32_e32 v46, 16, v47
	s_waitcnt lgkmcnt(0)
	v_fmamk_f32 v48, v52, 0x3a800000, v61
	v_mul_f32_e32 v49, 0x4f800000, v48
	v_cmp_gt_f32_e32 vcc, s5, v48
	v_and_b32_e32 v47, 0xffff0000, v47
	v_pk_mul_f32 v[46:47], v[72:73], v[46:47] op_sel_hi:[0,1]
	v_cndmask_b32_e32 v52, v48, v49, vcc
	v_sqrt_f32_e32 v53, v52
	v_pk_mul_f32 v[48:49], v[14:15], v[46:47]
	v_pk_mul_f32 v[46:47], v[12:13], v[50:51]
	v_add_u32_e32 v50, -1, v53
	v_fma_f32 v51, -v50, v53, v52
	v_cmp_ge_f32_e64 s[2:3], 0, v51
	v_add_u32_e32 v51, 1, v53
	s_nop 0
	v_cndmask_b32_e64 v50, v53, v50, s[2:3]
	v_fma_f32 v53, -v51, v53, v52
	v_cmp_lt_f32_e64 s[2:3], 0, v53
	s_nop 1
	v_cndmask_b32_e64 v50, v50, v51, s[2:3]
	v_mul_f32_e32 v51, 0x37800000, v50
	v_cndmask_b32_e32 v50, v50, v51, vcc
	v_cmp_class_f32_e32 vcc, v52, v62
	s_nop 1
	v_cndmask_b32_e32 v52, v50, v52, vcc
	v_div_scale_f32 v53, s[2:3], v52, v52, 1.0
	v_rcp_f32_e32 v54, v53
	v_add_co_u32_e32 v50, vcc, s14, v16
	s_nop 1
	v_addc_co_u32_e32 v51, vcc, -1, v17, vcc
	global_store_dwordx4 v[50:51], v[46:49], off offset:-4096 nt
	s_nop 1
	v_fma_f32 v46, -v53, v54, 1.0
	v_fmac_f32_e32 v54, v46, v54
	v_div_scale_f32 v46, vcc, 1.0, v52, 1.0
	v_mul_f32_e32 v47, v46, v54
	v_fma_f32 v48, -v53, v47, v46
	v_fmac_f32_e32 v47, v48, v54
	v_fma_f32 v46, -v53, v47, v46
	v_div_fmas_f32 v46, v46, v54, v47
	v_div_fixup_f32 v48, v46, v52, 1.0
	v_lshlrev_b32_e32 v46, 16, v44
	v_and_b32_e32 v47, 0xffff0000, v44
	v_lshlrev_b32_e32 v44, 16, v45
	v_and_b32_e32 v45, 0xffff0000, v45
	v_pk_mul_f32 v[52:53], v[48:49], v[46:47] op_sel_hi:[0,1]
	v_pk_mul_f32 v[44:45], v[48:49], v[44:45] op_sel_hi:[0,1]
	ds_bpermute_b32 v49, v56, v64
	v_pk_mul_f32 v[46:47], v[2:3], v[44:45]
	v_pk_mul_f32 v[44:45], v[0:1], v[52:53]
	global_store_dwordx4 v[50:51], v[44:47], off offset:-3072 nt
	s_nop 1
	v_lshlrev_b32_e32 v44, 16, v42
	v_and_b32_e32 v45, 0xffff0000, v42
	s_waitcnt lgkmcnt(0)
	v_pk_mul_f32 v[46:47], v[48:49], v[44:45] op_sel_hi:[0,1]
	v_add_f32_e32 v49, v64, v49
	ds_bpermute_b32 v52, v57, v49
	v_lshlrev_b32_e32 v42, 16, v43
	v_and_b32_e32 v43, 0xffff0000, v43
	v_pk_mul_f32 v[42:43], v[48:49], v[42:43] op_sel_hi:[0,1]
	v_pk_mul_f32 v[44:45], v[6:7], v[42:43]
	v_pk_mul_f32 v[42:43], v[4:5], v[46:47]
	global_store_dwordx4 v[50:51], v[42:45], off offset:-2048 nt
	s_waitcnt lgkmcnt(0)
; __device__ __forceinline__ float rs_of(float ss) { return 1.0f / sqrtf(ss * (1.f / 1024.f) + 1e-6f); }
; __device__ __forceinline__ void final_rows(const bf16_t* XB, float* out, const float* g, const float* SS, int gw, int NGW, int lane) {
;     ...
;     for (int m0 = 4 * gw; m0 < T; m0 += 4 * NGW) {
;     ...
; #pragma unroll
;         for (int q = 0; q < 4; ++q) { float t = tp[q]; t += __shfl_xor(t, 1); t += __shfl_xor(t, 2); t += __shfl_xor(t, 4); t += __shfl_xor(t, 8); const float r = rs_of(__shfl(t, 0));
;             f32x4* o = (f32x4*)(out + (size_t)(m0 + q) * D) + lane;
; #pragma unroll
;             for (int j = 0; j < 4; ++j) o[64 * j] = (f32x4){bf_lo(w[q][j].x), bf_hi(w[q][j].x), bf_lo(w[q][j].y), bf_hi(w[q][j].y)} * r * gv[j]; } }
	s_nop 0
	v_add_f32_e32 v44, v49, v52
	ds_bpermute_b32 v45, v58, v44
	v_lshlrev_b32_e32 v42, 16, v40
	v_and_b32_e32 v43, 0xffff0000, v40
	v_lshlrev_b32_e32 v40, 16, v41
	v_and_b32_e32 v41, 0xffff0000, v41
	s_waitcnt lgkmcnt(0)
	v_add_f32_e32 v46, v44, v45
	ds_bpermute_b32 v47, v59, v46
	v_pk_mul_f32 v[44:45], v[48:49], v[42:43] op_sel_hi:[0,1]
	v_pk_mul_f32 v[40:41], v[48:49], v[40:41] op_sel_hi:[0,1]
	v_pk_mul_f32 v[42:43], v[10:11], v[40:41]
	v_pk_mul_f32 v[40:41], v[8:9], v[44:45]
	s_waitcnt lgkmcnt(0)
	v_add_f32_e32 v44, v46, v47
	ds_bpermute_b32 v44, v60, v44
	global_store_dwordx4 v[50:51], v[40:43], off offset:-1024 nt
	s_nop 1
	v_lshlrev_b32_e32 v40, 16, v38
	s_waitcnt lgkmcnt(0)
	v_fmamk_f32 v42, v44, 0x3a800000, v61
	v_mul_f32_e32 v43, 0x4f800000, v42
	v_cmp_gt_f32_e32 vcc, s5, v42
	v_and_b32_e32 v41, 0xffff0000, v38
	v_lshlrev_b32_e32 v38, 16, v39
	v_cndmask_b32_e32 v44, v42, v43, vcc
	v_sqrt_f32_e32 v45, v44
	v_pk_mul_f32 v[42:43], v[48:49], v[40:41] op_sel_hi:[0,1]
	v_and_b32_e32 v39, 0xffff0000, v39
	v_pk_mul_f32 v[38:39], v[48:49], v[38:39] op_sel_hi:[0,1]
	v_add_u32_e32 v40, -1, v45
	v_fma_f32 v41, -v40, v45, v44
	v_cmp_ge_f32_e64 s[2:3], 0, v41
	v_add_u32_e32 v41, 1, v45
	s_nop 0
	v_cndmask_b32_e64 v40, v45, v40, s[2:3]
	v_fma_f32 v45, -v41, v45, v44
	v_cmp_lt_f32_e64 s[2:3], 0, v45
	s_nop 1
	v_cndmask_b32_e64 v40, v40, v41, s[2:3]
	v_mul_f32_e32 v41, 0x37800000, v40
	v_cndmask_b32_e32 v40, v40, v41, vcc
	v_cmp_class_f32_e32 vcc, v44, v62
	s_nop 1
	v_cndmask_b32_e32 v44, v40, v44, vcc
	v_div_scale_f32 v45, s[2:3], v44, v44, 1.0
	v_rcp_f32_e32 v46, v45
	v_pk_mul_f32 v[40:41], v[14:15], v[38:39]
	v_pk_mul_f32 v[38:39], v[12:13], v[42:43]
	global_store_dwordx4 v[50:51], v[38:41], off nt
	s_nop 1
	v_fma_f32 v38, -v45, v46, 1.0
	v_fmac_f32_e32 v46, v38, v46
	v_div_scale_f32 v38, vcc, 1.0, v44, 1.0
	v_mul_f32_e32 v39, v38, v46
	v_fma_f32 v40, -v45, v39, v38
	v_fmac_f32_e32 v39, v40, v46
	v_fma_f32 v38, -v45, v39, v38
	v_div_fmas_f32 v38, v38, v46, v39
	v_div_fixup_f32 v40, v38, v44, 1.0
	v_lshlrev_b32_e32 v38, 16, v36
	v_and_b32_e32 v39, 0xffff0000, v36
	v_lshlrev_b32_e32 v36, 16, v37
	v_and_b32_e32 v37, 0xffff0000, v37
	v_pk_mul_f32 v[42:43], v[40:41], v[38:39] op_sel_hi:[0,1]
	v_pk_mul_f32 v[36:37], v[40:41], v[36:37] op_sel_hi:[0,1]
	ds_bpermute_b32 v41, v56, v63
	v_pk_mul_f32 v[38:39], v[2:3], v[36:37]
	v_pk_mul_f32 v[36:37], v[0:1], v[42:43]
	v_add_co_u32_e32 v42, vcc, s15, v16
	s_nop 1
	v_addc_co_u32_e32 v43, vcc, -1, v17, vcc
	global_store_dwordx4 v[42:43], v[36:39], off offset:-3072 nt
	s_nop 1
	v_lshlrev_b32_e32 v36, 16, v34
	v_and_b32_e32 v37, 0xffff0000, v34
	s_waitcnt lgkmcnt(0)
	v_pk_mul_f32 v[38:39], v[40:41], v[36:37] op_sel_hi:[0,1]
	v_add_f32_e32 v41, v63, v41
	ds_bpermute_b32 v44, v57, v41
	v_lshlrev_b32_e32 v34, 16, v35
	v_and_b32_e32 v35, 0xffff0000, v35
	v_pk_mul_f32 v[34:35], v[40:41], v[34:35] op_sel_hi:[0,1]
	v_pk_mul_f32 v[36:37], v[6:7], v[34:35]
	v_pk_mul_f32 v[34:35], v[4:5], v[38:39]
	global_store_dwordx4 v[42:43], v[34:37], off offset:-2048 nt
	s_waitcnt lgkmcnt(0)
	s_nop 0
	v_add_f32_e32 v36, v41, v44
	ds_bpermute_b32 v37, v58, v36
	v_lshlrev_b32_e32 v34, 16, v32
	v_and_b32_e32 v35, 0xffff0000, v32
	v_lshlrev_b32_e32 v32, 16, v33
	v_and_b32_e32 v33, 0xffff0000, v33
	s_waitcnt lgkmcnt(0)
	v_add_f32_e32 v38, v36, v37
	ds_bpermute_b32 v39, v59, v38
	v_pk_mul_f32 v[36:37], v[40:41], v[34:35] op_sel_hi:[0,1]
	v_pk_mul_f32 v[32:33], v[40:41], v[32:33] op_sel_hi:[0,1]
	v_pk_mul_f32 v[34:35], v[10:11], v[32:33]
	v_pk_mul_f32 v[32:33], v[8:9], v[36:37]
	s_waitcnt lgkmcnt(0)
	v_add_f32_e32 v36, v38, v39
	ds_bpermute_b32 v36, v60, v36
	global_store_dwordx4 v[42:43], v[32:35], off offset:-1024 nt
	s_nop 1
	v_lshlrev_b32_e32 v32, 16, v30
	s_waitcnt lgkmcnt(0)
	v_fmamk_f32 v34, v36, 0x3a800000, v61
	v_mul_f32_e32 v35, 0x4f800000, v34
	v_cmp_gt_f32_e32 vcc, s5, v34
	v_and_b32_e32 v33, 0xffff0000, v30
	v_lshlrev_b32_e32 v30, 16, v31
	v_cndmask_b32_e32 v36, v34, v35, vcc
	v_sqrt_f32_e32 v37, v36
	v_pk_mul_f32 v[34:35], v[40:41], v[32:33] op_sel_hi:[0,1]
	v_and_b32_e32 v31, 0xffff0000, v31
	v_pk_mul_f32 v[30:31], v[40:41], v[30:31] op_sel_hi:[0,1]
	v_add_u32_e32 v32, -1, v37
	v_fma_f32 v33, -v32, v37, v36
	v_cmp_ge_f32_e64 s[2:3], 0, v33
	v_add_u32_e32 v33, 1, v37
	s_nop 0
	v_cndmask_b32_e64 v32, v37, v32, s[2:3]
	v_fma_f32 v37, -v33, v37, v36
	v_cmp_lt_f32_e64 s[2:3], 0, v37
	s_nop 1
	v_cndmask_b32_e64 v32, v32, v33, s[2:3]
	v_mul_f32_e32 v33, 0x37800000, v32
	v_cndmask_b32_e32 v32, v32, v33, vcc
	v_cmp_class_f32_e32 vcc, v36, v62
	s_nop 1
	v_cndmask_b32_e32 v36, v32, v36, vcc
	v_div_scale_f32 v37, s[2:3], v36, v36, 1.0
	v_rcp_f32_e32 v38, v37
	v_pk_mul_f32 v[32:33], v[14:15], v[30:31]
	v_pk_mul_f32 v[30:31], v[12:13], v[34:35]
	global_store_dwordx4 v[16:17], v[30:33], off offset:-4096 nt
	s_nop 1
	v_fma_f32 v30, -v37, v38, 1.0
	v_fmac_f32_e32 v38, v30, v38
	v_div_scale_f32 v30, vcc, 1.0, v36, 1.0
	v_mul_f32_e32 v31, v30, v38
	v_fma_f32 v32, -v37, v31, v30
	v_fmac_f32_e32 v31, v32, v38
	v_fma_f32 v30, -v37, v31, v30
	v_div_fmas_f32 v30, v30, v38, v31
	v_div_fixup_f32 v32, v30, v36, 1.0
	v_lshlrev_b32_e32 v30, 16, v28
	v_and_b32_e32 v31, 0xffff0000, v28
	v_lshlrev_b32_e32 v28, 16, v29
	v_and_b32_e32 v29, 0xffff0000, v29
	v_pk_mul_f32 v[34:35], v[32:33], v[30:31] op_sel_hi:[0,1]
	v_pk_mul_f32 v[28:29], v[32:33], v[28:29] op_sel_hi:[0,1]
	v_pk_mul_f32 v[30:31], v[2:3], v[28:29]
	v_pk_mul_f32 v[28:29], v[0:1], v[34:35]
	global_store_dwordx4 v[16:17], v[28:31], off offset:-3072 nt
	s_nop 1
	v_lshlrev_b32_e32 v28, 16, v26
	v_and_b32_e32 v29, 0xffff0000, v26
	v_lshlrev_b32_e32 v26, 16, v27
	v_and_b32_e32 v27, 0xffff0000, v27
	v_pk_mul_f32 v[30:31], v[32:33], v[28:29] op_sel_hi:[0,1]
	v_pk_mul_f32 v[26:27], v[32:33], v[26:27] op_sel_hi:[0,1]
	v_pk_mul_f32 v[28:29], v[6:7], v[26:27]
	v_pk_mul_f32 v[26:27], v[4:5], v[30:31]
	global_store_dwordx4 v[16:17], v[26:29], off offset:-2048 nt
	s_nop 1
	v_lshlrev_b32_e32 v26, 16, v24
	v_and_b32_e32 v27, 0xffff0000, v24
	v_lshlrev_b32_e32 v24, 16, v25
	v_and_b32_e32 v25, 0xffff0000, v25
	v_pk_mul_f32 v[28:29], v[32:33], v[26:27] op_sel_hi:[0,1]
	v_pk_mul_f32 v[24:25], v[32:33], v[24:25] op_sel_hi:[0,1]
	v_pk_mul_f32 v[26:27], v[10:11], v[24:25]
	v_pk_mul_f32 v[24:25], v[8:9], v[28:29]
	global_store_dwordx4 v[16:17], v[24:27], off offset:-1024 nt
	s_nop 1
	v_lshlrev_b32_e32 v24, 16, v22
	v_and_b32_e32 v25, 0xffff0000, v22
	v_lshlrev_b32_e32 v22, 16, v23
	v_and_b32_e32 v23, 0xffff0000, v23
	v_pk_mul_f32 v[26:27], v[32:33], v[24:25] op_sel_hi:[0,1]
	v_pk_mul_f32 v[22:23], v[32:33], v[22:23] op_sel_hi:[0,1]
	v_pk_mul_f32 v[24:25], v[14:15], v[22:23]
	v_pk_mul_f32 v[22:23], v[12:13], v[26:27]
	global_store_dwordx4 v[16:17], v[22:25], off nt
	v_lshl_add_u64 v[16:17], v[16:17], 0, s[8:9]
	s_cbranch_scc0 .LBB0_1914
